# band attention: the 32 per-tile moves of -1e30 into the score registers now run only on the (rare) masked path instead of before the branch on every tile
# baseline (speedup 1.0000x reference)
; #define LAS __attribute__((address_space(3)))
; #define SBAR() __builtin_amdgcn_sched_barrier(0)
; DI void finishSM(f32x16& p0, f32x16& p1, float alpha, float& l_reg, bf16x8& pa0, bf16x8& pa1, bf16x8& pa2, bf16x8& pa3) {
; #pragma unroll
;   for (int r = 0; r < 16; ++r) p1[r] = __builtin_amdgcn_exp2f(p1[r]);
;   float ps = 0;
; #pragma unroll
;   for (int r = 0; r < 16; ++r) ps += p0[r];
; #pragma unroll
;   for (int r = 0; r < 16; ++r) ps += p1[r];
;   { auto rr = __builtin_amdgcn_permlane32_swap(__float_as_uint(ps), __float_as_uint(ps), false, false);
;     ps = __uint_as_float(rr[0]) + __uint_as_float(rr[1]); }
;   l_reg = l_reg * alpha + ps;
;     ...
;   PK4(p0, 0, pa0); PK4(p0, 8, pa1); PK4(p1, 0, pa2); PK4(p1, 8, pa3);
;     ...
; }
; template <int NQ> DI void qkt(f32x16& p0, f32x16& p1, const LAS char* Ks, const LAS char* KRs, const bf16x8* qr, int r32, int hi) {
;   p0 = f32x16{}; p1 = f32x16{};
; #pragma unroll
;   for (int d0 = 0; d0 < 8; ++d0) { const int cb = (d0 * 16 + hi * 8) * 2;
;     const bf16x8 b0 = *(const LAS bf16x8*)(Ks + KSWZ(r32, cb));
;     const bf16x8 b1 = *(const LAS bf16x8*)(Ks + KSWZ(32 + r32, cb));
;     p0 = __builtin_amdgcn_mfma_f32_32x32x16_bf16(b0, qr[d0], p0, 0, 0, 0);
;     p1 = __builtin_amdgcn_mfma_f32_32x32x16_bf16(b1, qr[d0], p1, 0, 0, 0); }
; template <bool BAND, int SD, bool ACT> DI void attn_unit_(const Unit& U, LAS char* lds, float C) {
;     ...
;     if (ACT) { qkt<NQ>(pB0, pB1, K_lds + SHM_K, KR_lds + SHM_KR, qr, r32, hi); finishSM(pA0, pA1, alA, l_reg, pa0, pa1, pa2, pa3); }
;     SBAR();
;     SLOAD(SO, j + SD); SBAR();
;     if (ACT) { pv_d0(o, vb0, pa0, pa1, pa2, pa3); partialSM<BAND>(pB0, pB1, m_reg, mnB, alB, MASKED(j), T3 + jb0 + 64 * j, C); }
.LBB0_282:
	s_add_i32 s18, s49, -3
	ds_read_b128 v[80:83], v222 offset:58880
	ds_read_b128 v[84:87], v222 offset:50176
	ds_read_b128 v[192:195], v222 offset:50208
	ds_read_b128 v[196:199], v222 offset:58912
	v_exp_f32_e32 v200, v64
	v_add_f32_e32 v64, 0, v177
	s_waitcnt lgkmcnt(2)
	v_mfma_f32_32x32x16_bf16 v[96:111], v[84:87], v[144:147], 0
	v_add_f32_e32 v64, v179, v64
	v_add_f32_e32 v64, v175, v64
	v_add_f32_e32 v64, v178, v64
	v_add_f32_e32 v64, v174, v64
	v_add_f32_e32 v64, v176, v64
	v_add_f32_e32 v64, v172, v64
	v_add_f32_e32 v64, v173, v64
	v_mfma_f32_32x32x16_bf16 v[80:95], v[80:83], v[144:147], 0
	v_add_f32_e32 v64, v169, v64
	v_add_f32_e32 v64, v171, v64
	v_add_f32_e32 v64, v168, v64
	v_add_f32_e32 v64, v170, v64
	v_exp_f32_e32 v78, v78
	v_add_f32_e32 v64, v165, v64
	v_exp_f32_e32 v79, v79
	s_waitcnt lgkmcnt(1)
	v_mfma_f32_32x32x16_bf16 v[96:111], v[192:195], v[140:143], v[96:111]
	v_add_f32_e32 v64, v167, v64
	v_exp_f32_e32 v76, v76
	v_add_f32_e32 v64, v164, v64
	v_exp_f32_e32 v77, v77
	v_add_f32_e32 v64, v166, v64
	v_exp_f32_e32 v74, v74
	v_add_f32_e32 v64, v78, v64
	s_waitcnt lgkmcnt(0)
	v_mfma_f32_32x32x16_bf16 v[80:95], v[196:199], v[140:143], v[80:95]
	ds_read_b128 v[192:195], v222 offset:50240
	ds_read_b128 v[196:199], v222 offset:58944
	v_exp_f32_e32 v75, v75
	v_add_f32_e32 v64, v79, v64
	v_add_f32_e32 v64, v76, v64
	v_add_f32_e32 v64, v77, v64
	v_add_f32_e32 v64, v74, v64
	v_add_f32_e32 v64, v75, v64
	s_waitcnt lgkmcnt(1)
	v_mfma_f32_32x32x16_bf16 v[96:111], v[192:195], v[136:139], v[96:111]
	v_exp_f32_e32 v201, v65
	s_waitcnt lgkmcnt(0)
	v_mfma_f32_32x32x16_bf16 v[80:95], v[196:199], v[136:139], v[80:95]
	ds_read_b128 v[192:195], v222 offset:50272
	ds_read_b128 v[196:199], v222 offset:58976
	s_waitcnt lgkmcnt(1)
	v_mfma_f32_32x32x16_bf16 v[96:111], v[192:195], v[132:135], v[96:111]
	s_waitcnt lgkmcnt(0)
	v_mfma_f32_32x32x16_bf16 v[80:95], v[196:199], v[132:135], v[80:95]
	ds_read_b128 v[192:195], v222 offset:50304
	ds_read_b128 v[196:199], v222 offset:59008
	s_waitcnt lgkmcnt(1)
	v_mfma_f32_32x32x16_bf16 v[96:111], v[192:195], v[128:131], v[96:111]
	s_waitcnt lgkmcnt(0)
	v_mfma_f32_32x32x16_bf16 v[80:95], v[196:199], v[128:131], v[80:95]
	ds_read_b128 v[192:195], v222 offset:50336
	ds_read_b128 v[196:199], v222 offset:59040
	s_waitcnt lgkmcnt(1)
	v_mfma_f32_32x32x16_bf16 v[96:111], v[192:195], v[124:127], v[96:111]
	s_waitcnt lgkmcnt(0)
	v_mfma_f32_32x32x16_bf16 v[80:95], v[196:199], v[124:127], v[80:95]
	ds_read_b128 v[192:195], v222 offset:50368
	ds_read_b128 v[196:199], v222 offset:59072
	s_waitcnt lgkmcnt(1)
	v_mfma_f32_32x32x16_bf16 v[96:111], v[192:195], v[120:123], v[96:111]
	s_waitcnt lgkmcnt(0)
	v_mfma_f32_32x32x16_bf16 v[80:95], v[196:199], v[120:123], v[80:95]
	ds_read_b128 v[192:195], v222 offset:50400
	ds_read_b128 v[196:199], v222 offset:59104
	s_waitcnt lgkmcnt(1)
	v_mfma_f32_32x32x16_bf16 v[96:111], v[192:195], v[116:119], v[96:111]
	v_exp_f32_e32 v192, v72
	v_exp_f32_e32 v193, v73
	v_exp_f32_e32 v194, v70
	v_exp_f32_e32 v195, v71
	v_add_f32_e32 v64, v192, v64
	v_add_f32_e32 v64, v193, v64
	v_add_f32_e32 v64, v194, v64
	s_waitcnt lgkmcnt(0)
	v_mfma_f32_32x32x16_bf16 v[80:95], v[196:199], v[116:119], v[80:95]
	v_exp_f32_e32 v196, v68
	v_exp_f32_e32 v197, v69
	v_exp_f32_e32 v198, v66
	v_exp_f32_e32 v199, v67
	v_add_f32_e32 v64, v195, v64
	v_add_f32_e32 v64, v196, v64
	v_add_f32_e32 v64, v197, v64
	v_add_f32_e32 v64, v198, v64
	v_add_f32_e32 v64, v199, v64
	v_add_f32_e32 v64, v200, v64
	v_add_f32_e32 v232, v201, v64
	v_mov_b32_e32 v233, v232
	v_cvt_pk_bf16_f32 v64, v177, v179
	v_cvt_pk_bf16_f32 v65, v175, v178
	v_cvt_pk_bf16_f32 v66, v174, v176
	v_cvt_pk_bf16_f32 v67, v172, v173
	v_cvt_pk_bf16_f32 v68, v169, v171
	v_cvt_pk_bf16_f32 v69, v168, v170
	v_cvt_pk_bf16_f32 v70, v165, v167
	v_cvt_pk_bf16_f32 v71, v164, v166
	v_cvt_pk_bf16_f32 v72, v78, v79
	v_cvt_pk_bf16_f32 v73, v76, v77
	v_cvt_pk_bf16_f32 v74, v74, v75
	v_cvt_pk_bf16_f32 v75, v192, v193
	v_cvt_pk_bf16_f32 v76, v194, v195
	v_cvt_pk_bf16_f32 v77, v196, v197
	v_cvt_pk_bf16_f32 v78, v198, v199
	v_cvt_pk_bf16_f32 v79, v200, v201
	s_nop 1
	v_permlane32_swap_b32_e32 v232, v233
	v_permlane32_swap_b32_e32 v64, v66
	v_permlane32_swap_b32_e32 v65, v67
	v_permlane32_swap_b32_e32 v68, v70
	v_permlane32_swap_b32_e32 v69, v71
	v_permlane32_swap_b32_e32 v72, v74
	v_permlane32_swap_b32_e32 v73, v75
	v_permlane32_swap_b32_e32 v76, v78
	v_permlane32_swap_b32_e32 v77, v79
	s_add_i32 s16, s49, -1
	s_min_i32 s16, s16, s35
	s_ashr_i32 s17, s16, 31
	s_lshl_b64 s[16:17], s[16:17], 18
	s_add_u32 s22, s12, s16
	s_addc_u32 s23, s13, s17
	s_add_u32 s16, s14, s16
	s_addc_u32 s17, s15, s17
	v_lshl_add_u64 v[164:165], s[16:17], 0, v[112:113]
	v_lshl_add_u64 v[168:169], s[16:17], 0, v[114:115]
	v_lshl_add_u64 v[172:173], s[22:23], 0, v[112:113]
	v_lshl_add_u64 v[176:177], s[22:23], 0, v[114:115]
	global_load_dwordx4 v[164:167], v[164:165], off
	s_nop 0
	global_load_dwordx4 v[168:171], v[168:169], off
	s_nop 0
	global_load_dwordx4 v[172:175], v[172:173], off
	s_nop 0
	global_load_dwordx4 v[176:179], v[176:177], off
	ds_read_b64_tr_b16 v[192:193], v223 offset:0
	ds_read_b64_tr_b16 v[194:195], v223 offset:0x800
	ds_read_b64_tr_b16 v[196:197], v223 offset:0x1000
	ds_read_b64_tr_b16 v[198:199], v223 offset:0x1800
	ds_read_b64_tr_b16 v[200:201], v223 offset:0x2000
	ds_read_b64_tr_b16 v[202:203], v223 offset:0x2800
	ds_read_b64_tr_b16 v[204:205], v223 offset:0x3000
	ds_read_b64_tr_b16 v[206:207], v223 offset:0x3800
	s_waitcnt lgkmcnt(0)
; #define LAS __attribute__((address_space(3)))
; #define SBAR() __builtin_amdgcn_sched_barrier(0)
; template <int OFF> DI s16x4 tr_read(int vb) { s16x4 r; asm volatile("ds_read_b64_tr_b16 %0, %1 offset:%2" : "=&v"(r) : "v"(vb), "i"(OFF) : "memory"); return r; }
; template <bool BAND> DI void partialSM(f32x16& p0, f32x16& p1, float& m_reg, float& mn, float& alpha, bool masked, const LAS float* tb, float C) {
;   if (masked) {
; #pragma unroll
;     for (int r = 0; r < 16; ++r) { p0[r] = -1e30f; p1[r] = -1e30f; }
;   } else if (BAND) {
; #pragma unroll
;     for (int r = 0; r < 16; ++r) { const int ko = (r & 3) + 8 * (r >> 2); p0[r] = fmaf(p0[r], C, tb[ko]); }
;     SBAR();
; #pragma unroll
;     for (int r = 0; r < 16; ++r) { const int ko = (r & 3) + 8 * (r >> 2); p1[r] = fmaf(p1[r], C, tb[ko + 32]); }
; template <int D0> DI void pv_one(f32x16& od, int vb, bf16x8 pa0, bf16x8 pa1, bf16x8 pa2, bf16x8 pa3) {
;   const s16x4 l0 = tr_read<v_rd_off(D0, 0, 0)>(vb), h0 = tr_read<v_rd_off(D0, 0, 1)>(vb), l1 = tr_read<v_rd_off(D0, 1, 0)>(vb), h1 = tr_read<v_rd_off(D0, 1, 1)>(vb);
;   const s16x4 l2 = tr_read<v_rd_off(D0, 2, 0)>(vb), h2 = tr_read<v_rd_off(D0, 2, 1)>(vb), l3 = tr_read<v_rd_off(D0, 3, 0)>(vb), h3 = tr_read<v_rd_off(D0, 3, 1)>(vb);
;   asm volatile("s_waitcnt lgkmcnt(0)" ::: "memory"); SBAR();
;     ...
;   od = __builtin_amdgcn_mfma_f32_32x32x16_bf16(pa0, PK(l0, h0), od, 0, 0, 0);
;   od = __builtin_amdgcn_mfma_f32_32x32x16_bf16(pa1, PK(l1, h1), od, 0, 0, 0);
;   od = __builtin_amdgcn_mfma_f32_32x32x16_bf16(pa2, PK(l2, h2), od, 0, 0, 0);
;   od = __builtin_amdgcn_mfma_f32_32x32x16_bf16(pa3, PK(l3, h3), od, 0, 0, 0);
	s_nop 0
	v_mfma_f32_32x32x16_bf16 v[48:63], v[64:67], v[192:195], v[48:63]
	ds_read_b64_tr_b16 v[192:193], v223 offset:0x200
	ds_read_b64_tr_b16 v[194:195], v223 offset:0xa00
	v_mfma_f32_32x32x16_bf16 v[48:63], v[68:71], v[196:199], v[48:63]
	ds_read_b64_tr_b16 v[196:197], v223 offset:0x1200
	ds_read_b64_tr_b16 v[198:199], v223 offset:0x1a00
	v_mfma_f32_32x32x16_bf16 v[48:63], v[72:75], v[200:203], v[48:63]
	ds_read_b64_tr_b16 v[200:201], v223 offset:0x2200
	ds_read_b64_tr_b16 v[202:203], v223 offset:0x2a00
	v_mfma_f32_32x32x16_bf16 v[48:63], v[76:79], v[204:207], v[48:63]
	ds_read_b64_tr_b16 v[204:205], v223 offset:0x3200
	ds_read_b64_tr_b16 v[206:207], v223 offset:0x3a00
	s_waitcnt lgkmcnt(0)
	v_mfma_f32_32x32x16_bf16 v[32:47], v[64:67], v[192:195], v[32:47]
	ds_read_b64_tr_b16 v[192:193], v223 offset:0x400
	ds_read_b64_tr_b16 v[194:195], v223 offset:0xc00
	v_mfma_f32_32x32x16_bf16 v[32:47], v[68:71], v[196:199], v[32:47]
	ds_read_b64_tr_b16 v[196:197], v223 offset:0x1400
	ds_read_b64_tr_b16 v[198:199], v223 offset:0x1c00
	v_mfma_f32_32x32x16_bf16 v[32:47], v[72:75], v[200:203], v[32:47]
	ds_read_b64_tr_b16 v[200:201], v223 offset:0x2400
	ds_read_b64_tr_b16 v[202:203], v223 offset:0x2c00
	v_mfma_f32_32x32x16_bf16 v[32:47], v[76:79], v[204:207], v[32:47]
	ds_read_b64_tr_b16 v[204:205], v223 offset:0x3400
	ds_read_b64_tr_b16 v[206:207], v223 offset:0x3c00
	s_waitcnt lgkmcnt(0)
	v_mfma_f32_32x32x16_bf16 v[16:31], v[64:67], v[192:195], v[16:31]
	ds_read_b64_tr_b16 v[192:193], v223 offset:0x600
	ds_read_b64_tr_b16 v[194:195], v223 offset:0xe00
	v_mfma_f32_32x32x16_bf16 v[16:31], v[68:71], v[196:199], v[16:31]
	ds_read_b64_tr_b16 v[196:197], v223 offset:0x1600
	ds_read_b64_tr_b16 v[198:199], v223 offset:0x1e00
	v_mfma_f32_32x32x16_bf16 v[16:31], v[72:75], v[200:203], v[16:31]
	ds_read_b64_tr_b16 v[200:201], v223 offset:0x2600
	ds_read_b64_tr_b16 v[202:203], v223 offset:0x2e00
	v_mfma_f32_32x32x16_bf16 v[16:31], v[76:79], v[204:207], v[16:31]
	ds_read_b64_tr_b16 v[204:205], v223 offset:0x3600
	ds_read_b64_tr_b16 v[206:207], v223 offset:0x3e00
	s_waitcnt lgkmcnt(0)
	v_mfma_f32_32x32x16_bf16 v[0:15], v[64:67], v[192:195], v[0:15]
	s_cmp_gt_i32 s34, s18
	s_cselect_b64 s[16:17], -1, 0
	s_cmp_gt_i32 s18, s25
	s_cselect_b64 s[22:23], -1, 0
	s_or_b64 s[16:17], s[16:17], s[22:23]
	s_and_b64 vcc, exec, s[16:17]
	v_mfma_f32_32x32x16_bf16 v[0:15], v[68:71], v[196:199], v[0:15]
	v_mfma_f32_32x32x16_bf16 v[0:15], v[72:75], v[200:203], v[0:15]
	v_mfma_f32_32x32x16_bf16 v[0:15], v[76:79], v[204:207], v[0:15]
	s_cbranch_vccnz .Lband_msk1
	ds_read2_b32 v[64:65], v231 offset0:16 offset1:17
	ds_read2_b32 v[66:67], v231 offset0:18 offset1:19
	ds_read2_b32 v[68:69], v231 offset0:24 offset1:25
	ds_read2_b32 v[70:71], v231 offset0:26 offset1:27
	ds_read2_b32 v[72:73], v231 offset1:1
	ds_read2_b32 v[74:75], v231 offset0:2 offset1:3
	ds_read2_b32 v[76:77], v231 offset0:8 offset1:9
	ds_read2_b32 v[78:79], v231 offset0:10 offset1:11
	s_waitcnt lgkmcnt(4)
	v_pk_fma_f32 v[192:193], v[110:111], s[36:37], v[70:71] op_sel_hi:[1,0,1]
	v_pk_fma_f32 v[194:195], v[108:109], s[36:37], v[68:69] op_sel_hi:[1,0,1]
	v_pk_fma_f32 v[196:197], v[106:107], s[36:37], v[66:67] op_sel_hi:[1,0,1]
	v_pk_fma_f32 v[198:199], v[104:105], s[36:37], v[64:65] op_sel_hi:[1,0,1]
	s_waitcnt lgkmcnt(0)
	v_pk_fma_f32 v[202:203], v[102:103], s[36:37], v[78:79] op_sel_hi:[1,0,1]
	v_pk_fma_f32 v[200:201], v[100:101], s[36:37], v[76:77] op_sel_hi:[1,0,1]
	v_pk_fma_f32 v[204:205], v[98:99], s[36:37], v[74:75] op_sel_hi:[1,0,1]
	v_pk_fma_f32 v[206:207], v[96:97], s[36:37], v[72:73] op_sel_hi:[1,0,1]
	ds_read2_b32 v[68:69], v231 offset0:48 offset1:49
	ds_read2_b32 v[70:71], v231 offset0:50 offset1:51
	ds_read2_b32 v[64:65], v231 offset0:56 offset1:57
	ds_read2_b32 v[66:67], v231 offset0:58 offset1:59
	ds_read2_b32 v[96:97], v231 offset0:32 offset1:33
	ds_read2_b32 v[78:79], v231 offset0:34 offset1:35
	ds_read2_b32 v[76:77], v231 offset0:40 offset1:41
	ds_read2_b32 v[72:73], v231 offset0:42 offset1:43
	s_waitcnt lgkmcnt(4)
	v_pk_fma_f32 v[66:67], v[94:95], s[36:37], v[66:67] op_sel_hi:[1,0,1]
	v_pk_fma_f32 v[64:65], v[92:93], s[36:37], v[64:65] op_sel_hi:[1,0,1]
	v_pk_fma_f32 v[70:71], v[90:91], s[36:37], v[70:71] op_sel_hi:[1,0,1]
	v_pk_fma_f32 v[74:75], v[88:89], s[36:37], v[68:69] op_sel_hi:[1,0,1]
	s_waitcnt lgkmcnt(0)
	v_pk_fma_f32 v[72:73], v[86:87], s[36:37], v[72:73] op_sel_hi:[1,0,1]
	v_pk_fma_f32 v[76:77], v[84:85], s[36:37], v[76:77] op_sel_hi:[1,0,1]
	v_pk_fma_f32 v[78:79], v[82:83], s[36:37], v[78:79] op_sel_hi:[1,0,1]
	v_pk_fma_f32 v[68:69], v[80:81], s[36:37], v[96:97] op_sel_hi:[1,0,1]

; #define LAS __attribute__((address_space(3)))
; #define SBAR() __builtin_amdgcn_sched_barrier(0)
; template <int OFF> DI s16x4 tr_read(int vb) { s16x4 r; asm volatile("ds_read_b64_tr_b16 %0, %1 offset:%2" : "=&v"(r) : "v"(vb), "i"(OFF) : "memory"); return r; }
; template <bool BAND> DI void partialSM(f32x16& p0, f32x16& p1, float& m_reg, float& mn, float& alpha, bool masked, const LAS float* tb, float C) {
;   if (masked) {
; #pragma unroll
;     for (int r = 0; r < 16; ++r) { p0[r] = -1e30f; p1[r] = -1e30f; }
;   } else if (BAND) {
; #pragma unroll
;     for (int r = 0; r < 16; ++r) { const int ko = (r & 3) + 8 * (r >> 2); p0[r] = fmaf(p0[r], C, tb[ko]); }
;     SBAR();
; #pragma unroll
;     for (int r = 0; r < 16; ++r) { const int ko = (r & 3) + 8 * (r >> 2); p1[r] = fmaf(p1[r], C, tb[ko + 32]); }
; template <int D0> DI void pv_one(f32x16& od, int vb, bf16x8 pa0, bf16x8 pa1, bf16x8 pa2, bf16x8 pa3) {
;   const s16x4 l0 = tr_read<v_rd_off(D0, 0, 0)>(vb), h0 = tr_read<v_rd_off(D0, 0, 1)>(vb), l1 = tr_read<v_rd_off(D0, 1, 0)>(vb), h1 = tr_read<v_rd_off(D0, 1, 1)>(vb);
;   const s16x4 l2 = tr_read<v_rd_off(D0, 2, 0)>(vb), h2 = tr_read<v_rd_off(D0, 2, 1)>(vb), l3 = tr_read<v_rd_off(D0, 3, 0)>(vb), h3 = tr_read<v_rd_off(D0, 3, 1)>(vb);
;   asm volatile("s_waitcnt lgkmcnt(0)" ::: "memory"); SBAR();
;     ...
;   od = __builtin_amdgcn_mfma_f32_32x32x16_bf16(pa0, PK(l0, h0), od, 0, 0, 0);
;   od = __builtin_amdgcn_mfma_f32_32x32x16_bf16(pa1, PK(l1, h1), od, 0, 0, 0);
;   od = __builtin_amdgcn_mfma_f32_32x32x16_bf16(pa2, PK(l2, h2), od, 0, 0, 0);
;   od = __builtin_amdgcn_mfma_f32_32x32x16_bf16(pa3, PK(l3, h3), od, 0, 0, 0);
; template <bool BAND, int SD, bool ACT> DI void attn_unit_(const Unit& U, LAS char* lds, float C) {
;     ...
;     if (ACT) { pv_d0(o, vb0 + SHM_V, pa0, pa1, pa2, pa3); partialSM<BAND>(pA0, pA1, m_reg, mnA, alA, MASKED(j + 1), T3 + jb0 + 64 * (j + 1), C); }
.LBB0_290:
	s_add_i32 s19, s49, -2
	ds_read_b64_tr_b16 v[192:193], v230 offset:0
	ds_read_b64_tr_b16 v[194:195], v230 offset:0x800
	ds_read_b64_tr_b16 v[196:197], v230 offset:0x1000
	ds_read_b64_tr_b16 v[198:199], v230 offset:0x1800
	ds_read_b64_tr_b16 v[200:201], v230 offset:0x2000
	ds_read_b64_tr_b16 v[202:203], v230 offset:0x2800
	ds_read_b64_tr_b16 v[204:205], v230 offset:0x3000
	ds_read_b64_tr_b16 v[206:207], v230 offset:0x3800
	s_waitcnt lgkmcnt(0)
	s_nop 0
	v_mfma_f32_32x32x16_bf16 v[48:63], v[96:99], v[192:195], v[48:63]
	ds_read_b64_tr_b16 v[192:193], v230 offset:0x200
	ds_read_b64_tr_b16 v[194:195], v230 offset:0xa00
	v_mfma_f32_32x32x16_bf16 v[48:63], v[100:103], v[196:199], v[48:63]
	ds_read_b64_tr_b16 v[196:197], v230 offset:0x1200
	ds_read_b64_tr_b16 v[198:199], v230 offset:0x1a00
	v_mfma_f32_32x32x16_bf16 v[48:63], v[104:107], v[200:203], v[48:63]
	ds_read_b64_tr_b16 v[200:201], v230 offset:0x2200
	ds_read_b64_tr_b16 v[202:203], v230 offset:0x2a00
	v_mfma_f32_32x32x16_bf16 v[48:63], v[108:111], v[204:207], v[48:63]
	ds_read_b64_tr_b16 v[204:205], v230 offset:0x3200
	ds_read_b64_tr_b16 v[206:207], v230 offset:0x3a00
	s_waitcnt lgkmcnt(0)
	v_mfma_f32_32x32x16_bf16 v[32:47], v[96:99], v[192:195], v[32:47]
	ds_read_b64_tr_b16 v[192:193], v230 offset:0x400
	ds_read_b64_tr_b16 v[194:195], v230 offset:0xc00
	v_mfma_f32_32x32x16_bf16 v[32:47], v[100:103], v[196:199], v[32:47]
	ds_read_b64_tr_b16 v[196:197], v230 offset:0x1400
	ds_read_b64_tr_b16 v[198:199], v230 offset:0x1c00
	v_mfma_f32_32x32x16_bf16 v[32:47], v[104:107], v[200:203], v[32:47]
	ds_read_b64_tr_b16 v[200:201], v230 offset:0x2400
	ds_read_b64_tr_b16 v[202:203], v230 offset:0x2c00
	v_mfma_f32_32x32x16_bf16 v[32:47], v[108:111], v[204:207], v[32:47]
	ds_read_b64_tr_b16 v[204:205], v230 offset:0x3400
	ds_read_b64_tr_b16 v[206:207], v230 offset:0x3c00
	s_waitcnt lgkmcnt(0)
	v_mfma_f32_32x32x16_bf16 v[16:31], v[96:99], v[192:195], v[16:31]
	ds_read_b64_tr_b16 v[192:193], v230 offset:0x600
	ds_read_b64_tr_b16 v[194:195], v230 offset:0xe00
	v_mfma_f32_32x32x16_bf16 v[16:31], v[100:103], v[196:199], v[16:31]
	ds_read_b64_tr_b16 v[196:197], v230 offset:0x1600
	ds_read_b64_tr_b16 v[198:199], v230 offset:0x1e00
	v_mfma_f32_32x32x16_bf16 v[16:31], v[104:107], v[200:203], v[16:31]
	ds_read_b64_tr_b16 v[200:201], v230 offset:0x2600
	ds_read_b64_tr_b16 v[202:203], v230 offset:0x2e00
	v_mfma_f32_32x32x16_bf16 v[16:31], v[108:111], v[204:207], v[16:31]
	ds_read_b64_tr_b16 v[204:205], v230 offset:0x3600
	ds_read_b64_tr_b16 v[206:207], v230 offset:0x3e00
	s_waitcnt lgkmcnt(0)
	v_mfma_f32_32x32x16_bf16 v[0:15], v[96:99], v[192:195], v[0:15]
	s_cmp_gt_i32 s34, s19
	s_cselect_b64 s[22:23], -1, 0
	s_cmp_ge_i32 s18, s25
	s_cselect_b64 s[18:19], -1, 0
	s_or_b64 s[18:19], s[22:23], s[18:19]
	s_and_b64 vcc, exec, s[18:19]
	v_mfma_f32_32x32x16_bf16 v[0:15], v[100:103], v[196:199], v[0:15]
	v_mfma_f32_32x32x16_bf16 v[0:15], v[104:107], v[200:203], v[0:15]
	v_mfma_f32_32x32x16_bf16 v[0:15], v[108:111], v[204:207], v[0:15]
	s_cbranch_vccnz .Lband_msk0
	ds_read2_b32 v[96:97], v231 offset0:80 offset1:81
	ds_read2_b32 v[98:99], v231 offset0:82 offset1:83
	ds_read2_b32 v[100:101], v231 offset0:88 offset1:89
	ds_read2_b32 v[102:103], v231 offset0:90 offset1:91
	ds_read2_b32 v[104:105], v231 offset0:64 offset1:65
	ds_read2_b32 v[106:107], v231 offset0:66 offset1:67
	ds_read2_b32 v[108:109], v231 offset0:72 offset1:73
	ds_read2_b32 v[110:111], v231 offset0:74 offset1:75
	s_waitcnt lgkmcnt(4)
	v_pk_fma_f32 v[192:193], v[94:95], s[36:37], v[102:103] op_sel_hi:[1,0,1]
	v_pk_fma_f32 v[194:195], v[92:93], s[36:37], v[100:101] op_sel_hi:[1,0,1]
	v_pk_fma_f32 v[196:197], v[90:91], s[36:37], v[98:99] op_sel_hi:[1,0,1]
	v_pk_fma_f32 v[198:199], v[88:89], s[36:37], v[96:97] op_sel_hi:[1,0,1]
	s_waitcnt lgkmcnt(0)
	v_pk_fma_f32 v[202:203], v[86:87], s[36:37], v[110:111] op_sel_hi:[1,0,1]
	v_pk_fma_f32 v[200:201], v[84:85], s[36:37], v[108:109] op_sel_hi:[1,0,1]
	v_pk_fma_f32 v[204:205], v[82:83], s[36:37], v[106:107] op_sel_hi:[1,0,1]
	v_pk_fma_f32 v[206:207], v[80:81], s[36:37], v[104:105] op_sel_hi:[1,0,1]
	ds_read2_b32 v[80:81], v231 offset0:112 offset1:113
	ds_read2_b32 v[82:83], v231 offset0:114 offset1:115
	ds_read2_b32 v[84:85], v231 offset0:120 offset1:121
	ds_read2_b32 v[86:87], v231 offset0:122 offset1:123
	ds_read2_b32 v[88:89], v231 offset0:96 offset1:97
	ds_read2_b32 v[90:91], v231 offset0:98 offset1:99
	ds_read2_b32 v[92:93], v231 offset0:104 offset1:105
	ds_read2_b32 v[94:95], v231 offset0:106 offset1:107
	s_waitcnt lgkmcnt(4)
	v_pk_fma_f32 v[110:111], v[78:79], s[36:37], v[86:87] op_sel_hi:[1,0,1]
	v_pk_fma_f32 v[108:109], v[76:77], s[36:37], v[84:85] op_sel_hi:[1,0,1]
	v_pk_fma_f32 v[106:107], v[74:75], s[36:37], v[82:83] op_sel_hi:[1,0,1]
	v_pk_fma_f32 v[104:105], v[72:73], s[36:37], v[80:81] op_sel_hi:[1,0,1]
	s_waitcnt lgkmcnt(0)
	v_pk_fma_f32 v[102:103], v[70:71], s[36:37], v[94:95] op_sel_hi:[1,0,1]
	v_pk_fma_f32 v[100:101], v[68:69], s[36:37], v[92:93] op_sel_hi:[1,0,1]
	v_pk_fma_f32 v[98:99], v[66:67], s[36:37], v[90:91] op_sel_hi:[1,0,1]
	v_pk_fma_f32 v[96:97], v[64:65], s[36:37], v[88:89] op_sel_hi:[1,0,1]

; template <bool BAND> DI void partialSM(f32x16& p0, f32x16& p1, float& m_reg, float& mn, float& alpha, bool masked, const LAS float* tb, float C) {
;   if (masked) {
; #pragma unroll
;     for (int r = 0; r < 16; ++r) { p0[r] = -1e30f; p1[r] = -1e30f; }
.Lband_msk0:
	v_mov_b32_e32 v96, 0xf149f2ca
	v_mov_b32_e32 v97, 0xf149f2ca
	v_mov_b32_e32 v98, 0xf149f2ca
	v_mov_b32_e32 v99, 0xf149f2ca
	v_mov_b32_e32 v100, 0xf149f2ca
	v_mov_b32_e32 v101, 0xf149f2ca
	v_mov_b32_e32 v102, 0xf149f2ca
	v_mov_b32_e32 v103, 0xf149f2ca
	v_mov_b32_e32 v104, 0xf149f2ca
	v_mov_b32_e32 v105, 0xf149f2ca
	v_mov_b32_e32 v106, 0xf149f2ca
	v_mov_b32_e32 v107, 0xf149f2ca
	v_mov_b32_e32 v200, 0xf149f2ca
	v_mov_b32_e32 v201, 0xf149f2ca
	v_mov_b32_e32 v202, 0xf149f2ca
	v_mov_b32_e32 v108, 0xf149f2ca
	v_mov_b32_e32 v109, 0xf149f2ca
	v_mov_b32_e32 v110, 0xf149f2ca
	v_mov_b32_e32 v111, 0xf149f2ca
	v_mov_b32_e32 v206, 0xf149f2ca
	v_mov_b32_e32 v207, 0xf149f2ca
	v_mov_b32_e32 v204, 0xf149f2ca
	v_mov_b32_e32 v205, 0xf149f2ca
	v_mov_b32_e32 v203, 0xf149f2ca
	v_mov_b32_e32 v198, 0xf149f2ca
	v_mov_b32_e32 v199, 0xf149f2ca
	v_mov_b32_e32 v196, 0xf149f2ca
	v_mov_b32_e32 v197, 0xf149f2ca
	v_mov_b32_e32 v194, 0xf149f2ca
	v_mov_b32_e32 v195, 0xf149f2ca
	v_mov_b32_e32 v192, 0xf149f2ca
	v_mov_b32_e32 v193, 0xf149f2ca
	s_branch .LBB0_292
.Lband_msk1:
	v_mov_b32_e32 v64, 0xf149f2ca
	v_mov_b32_e32 v68, 0xf149f2ca
	v_mov_b32_e32 v69, 0xf149f2ca
	v_mov_b32_e32 v70, 0xf149f2ca
	v_mov_b32_e32 v71, 0xf149f2ca
	v_mov_b32_e32 v65, 0xf149f2ca
	v_mov_b32_e32 v66, 0xf149f2ca
	v_mov_b32_e32 v67, 0xf149f2ca
	v_mov_b32_e32 v72, 0xf149f2ca
	v_mov_b32_e32 v73, 0xf149f2ca
	v_mov_b32_e32 v74, 0xf149f2ca
	v_mov_b32_e32 v75, 0xf149f2ca
	v_mov_b32_e32 v200, 0xf149f2ca
	v_mov_b32_e32 v201, 0xf149f2ca
	v_mov_b32_e32 v202, 0xf149f2ca
	v_mov_b32_e32 v78, 0xf149f2ca
	v_mov_b32_e32 v79, 0xf149f2ca
	v_mov_b32_e32 v76, 0xf149f2ca
	v_mov_b32_e32 v77, 0xf149f2ca
	v_mov_b32_e32 v206, 0xf149f2ca
	v_mov_b32_e32 v207, 0xf149f2ca
	v_mov_b32_e32 v204, 0xf149f2ca
	v_mov_b32_e32 v205, 0xf149f2ca
	v_mov_b32_e32 v203, 0xf149f2ca
	v_mov_b32_e32 v198, 0xf149f2ca
	v_mov_b32_e32 v199, 0xf149f2ca
	v_mov_b32_e32 v196, 0xf149f2ca
	v_mov_b32_e32 v197, 0xf149f2ca
	v_mov_b32_e32 v194, 0xf149f2ca
	v_mov_b32_e32 v195, 0xf149f2ca
	v_mov_b32_e32 v192, 0xf149f2ca
	v_mov_b32_e32 v193, 0xf149f2ca
	s_branch .LBB0_284
